# fast path v3: + back-edge rotation (next-iteration bookkeeping and K/V prefetch issue moved before the fast path's barrier)
# speedup vs baseline: 1.0018x; 1.0018x over previous
; DI void attn_item(const Params& p, int g, int seq, int hd, int qt, int m, char* smem, int split_j, int sub) {
;     ...
;   auto load_tile = [&](int t, u32x4& k, u32x4& v0, u32x4& v1) __attribute__((always_inline)) {
;     k = *(const u32x4*)(ksrc + (size_t)(tbase + t) * 2048);
;     v0 = *(const u32x4*)(vsrc + (size_t)(tbase + t) * 4096); v1 = *(const u32x4*)(vsrc + (size_t)(tbase + t) * 4096 + 2048);
;   };
;     ...
;   for (int it = 0; it < npairs; ++it) {
;     const int set = it & 1;
;     if (it + 1 < npairs) { load_tile(2 * it + 2, rkA, rvA0, rvA1); load_tile(2 * it + 3, rkB, rvB0, rvB1); }
;     compute(2 * it, 2 * set);
;     compute(2 * it + 1, 2 * set + 1);
;     if (it + 1 < npairs) { store_tile(2 * (set ^ 1), rkA, rvA0, rvA1); store_tile(2 * (set ^ 1) + 1, rkB, rvB0, rvB1); }
;     __syncthreads();
.Lat2_bot:
	s_add_i32 s13, s13, 64
	s_add_i32 s6, s6, 2
	s_cmp_lg_u32 s73, s15
	s_cbranch_scc0 .Lat2_exit
	s_add_i32 s15, s15, 1
	s_cmp_lt_u32 s15, s73
	s_cselect_b64 s[8:9], -1, 0
	s_cmp_ge_u32 s15, s73
	s_cbranch_scc1 .Lat2_nopf
	s_add_i32 s50, s6, -1
	s_lshl_b64 s[10:11], s[50:51], 12
	v_lshl_add_u64 v[236:237], v[172:173], 0, s[10:11]
	s_lshl_b64 s[10:11], s[50:51], 13
	v_lshl_add_u64 v[238:239], v[170:171], 0, s[10:11]
	s_mov_b32 s7, s51
	global_load_dwordx4 v[96:99], v[236:237], off
	global_load_dwordx4 v[100:103], v[238:239], off
	v_add_co_u32_e32 v236, vcc, 0x1000, v238
	s_lshl_b64 s[10:11], s[6:7], 12
	s_nop 0
	v_addc_co_u32_e32 v237, vcc, 0, v239, vcc
	v_lshl_add_u64 v[238:239], v[172:173], 0, s[10:11]
	s_lshl_b64 s[10:11], s[6:7], 13
	global_load_dwordx4 v[120:123], v[236:237], off
	global_load_dwordx4 v[124:127], v[238:239], off
	v_lshl_add_u64 v[236:237], v[170:171], 0, s[10:11]
	v_add_co_u32_e32 v238, vcc, 0x1000, v236
	s_nop 1
	v_addc_co_u32_e32 v239, vcc, 0, v237, vcc
	global_load_dwordx4 v[128:131], v[236:237], off
	global_load_dwordx4 v[132:135], v[238:239], off

; DI void attn_item(const Params& p, int g, int seq, int hd, int qt, int m, char* smem, int split_j, int sub) {
;     ...
;   for (int it = 0; it < npairs; ++it) {
;     const int set = it & 1;
;     if (it + 1 < npairs) { load_tile(2 * it + 2, rkA, rvA0, rvA1); load_tile(2 * it + 3, rkB, rvB0, rvB1); }
;     compute(2 * it, 2 * set);
;     compute(2 * it + 1, 2 * set + 1);
;     if (it + 1 < npairs) { store_tile(2 * (set ^ 1), rkA, rvA0, rvA1); store_tile(2 * (set ^ 1) + 1, rkB, rvB0, rvB1); }
;     __syncthreads();
;   }
.Lat2_exit:
	s_waitcnt lgkmcnt(0)
	s_barrier
	s_branch .LBB0_337
.LBB0_316:
	v_pk_add_f32 v[64:65], v[186:187], v[64:65]
	s_add_i32 s13, s13, 64
	v_pk_add_f32 v[64:65], v[66:67], v[64:65]
	s_add_i32 s6, s6, 2
	v_pk_add_f32 v[64:65], v[68:69], v[64:65]
	s_cmp_lg_u32 s73, s15
	v_pk_add_f32 v[64:65], v[70:71], v[64:65]
	s_waitcnt lgkmcnt(0)
	v_pk_add_f32 v[64:65], v[72:73], v[64:65]
	s_barrier
	v_pk_add_f32 v[64:65], v[74:75], v[64:65]
	s_nop 0
	v_pk_add_f32 v[64:65], v[76:77], v[64:65]
	s_nop 0
	v_pk_add_f32 v[186:187], v[78:79], v[64:65]
	s_cbranch_scc0 .LBB0_337
